# load de-serialisation stacked: EpiRes and GLU epilogues, layer-input rownorm bf16 path, conv taps and gate load, attention q-gain loads all issued together per trip (one memory round trip instead of 3
# speedup vs baseline: 1.0124x; 1.0111x over previous
; __device__ __forceinline__ void unpack8(u32x4 w, float* f) { f[0] = bflo(w.x); f[1] = bfhi(w.x); f[2] = bflo(w.y); f[3] = bfhi(w.y); f[4] = bflo(w.z); f[5] = bfhi(w.z); f[6] = bflo(w.w); f[7] = bfhi(w.w); }
; __device__ __forceinline__ void conv_phase(CArgs a, int l, int lane, int gw, int NGW) {
;     ...
;     for (int tok = gw; tok < T; tok += NGW) {
;         const bool pr = tok < TP; const int tl = pr ? (tok & (SEQ - 1)) : ((tok - TP) & 63); const int sb = pr ? 0 : ((tok - TP) >> 6);
;         float z[3][8];
; #pragma unroll
;         for (int k = 0; k < 3; ++k) {
;             if (tl - k >= 0) { const bf16_t* r = PROJ + (size_t)(tok - k) * NPJ; float gc[8], xc[8]; unpack8(*(const u32x4*)(r + PJ_GC + ch), gc); unpack8(*(const u32x4*)(r + PJ_XC + ch), xc);
; #pragma unroll
;                 for (int j = 0; j < 8; ++j) z[k][j] = gc[j] * xc[j];
;     ...
;         float gb[8]; unpack8(*(const u32x4*)(PROJ + (size_t)tok * NPJ + PJ_GB + ch), gb);
.LBB0_367:
	global_load_dwordx4 v[34:37], v[64:65], off offset:1024
	global_load_dwordx4 v[30:33], v[64:65], off offset:2048
	s_cmpk_gt_i32 s15, 0x7fff
	s_mov_b32 s24, s8
	s_cselect_b64 s[8:9], -1, 0
	s_and_b32 s16, s15, 0x3fff
	s_and_b32 s17, s15, 63
	s_cmp_lt_i32 s15, 0x8000
	s_cselect_b64 s[10:11], -1, 0
	s_and_b64 s[0:1], s[10:11], exec
	s_cselect_b32 s18, s16, s17
	s_cmp_gt_u32 s18, 1
	s_cbranch_scc0 .Lconv_no2
	s_mov_b32 s40, 0xffffd400
	s_mov_b32 s41, -1
	v_lshl_add_u64 v[74:75], v[64:65], 0, s[40:41]
	global_load_dwordx4 v[76:79], v[74:75], off offset:1024
	global_load_dwordx4 v[80:83], v[74:75], off offset:2048
.Lconv_no2:
	global_load_dwordx4 v[84:87], v[64:65], off
	s_cmp_lg_u32 s18, 0
	v_lshlrev_b32_e32 v160, 1, v46
	s_cbranch_scc0 .LBB0_369
	s_add_i32 s0, s15, -1
	s_mul_hi_i32 s1, s0, 0x1600
	s_mulk_i32 s0, 0x1600
	v_readlane_b32 s2, v255, 25
	v_readlane_b32 s3, v255, 26
	s_add_u32 s0, s2, s0
	s_addc_u32 s1, s3, s1
	v_lshl_add_u64 v[14:15], s[0:1], 0, v[160:161]
	v_add_co_u32_e32 v14, vcc, s86, v14
	global_load_dwordx4 v[22:25], v160, s[0:1] offset:3584
	s_nop 0
	v_addc_co_u32_e32 v15, vcc, 0, v15, vcc
	global_load_dwordx4 v[26:29], v[14:15], off offset:512
	s_mov_b64 s[0:1], 0
	s_waitcnt vmcnt(1)
	v_lshlrev_b32_e32 v14, 16, v22
	v_and_b32_e32 v15, 0xffff0000, v22
	s_waitcnt vmcnt(0)
	v_lshlrev_b32_e32 v16, 16, v26
	v_and_b32_e32 v17, 0xffff0000, v26
	v_pk_mul_f32 v[14:15], v[14:15], v[16:17]
	v_lshlrev_b32_e32 v16, 16, v23
	v_and_b32_e32 v17, 0xffff0000, v23
	v_lshlrev_b32_e32 v22, 16, v27
	v_and_b32_e32 v23, 0xffff0000, v27
	v_pk_mul_f32 v[16:17], v[16:17], v[22:23]
	v_lshlrev_b32_e32 v22, 16, v24
	v_and_b32_e32 v23, 0xffff0000, v24
	v_lshlrev_b32_e32 v26, 16, v28
	v_and_b32_e32 v27, 0xffff0000, v28
	v_pk_mul_f32 v[22:23], v[22:23], v[26:27]
	v_lshlrev_b32_e32 v24, 16, v25
	v_and_b32_e32 v25, 0xffff0000, v25
	v_lshlrev_b32_e32 v26, 16, v29
	v_and_b32_e32 v27, 0xffff0000, v29
	v_pk_mul_f32 v[24:25], v[24:25], v[26:27]
	s_branch .LBB0_370

; __device__ __forceinline__ unsigned pk2(float lo, float hi) { const f32x2 v = {lo, hi}; return __builtin_bit_cast(unsigned, __builtin_convertvector(v, bf16x2_t)); }
; __device__ __forceinline__ void unpack8(u32x4 w, float* f) { f[0] = bflo(w.x); f[1] = bfhi(w.x); f[2] = bflo(w.y); f[3] = bfhi(w.y); f[4] = bflo(w.z); f[5] = bfhi(w.z); f[6] = bflo(w.w); f[7] = bfhi(w.w); }
; __device__ __forceinline__ void conv_phase(CArgs a, int l, int lane, int gw, int NGW) {
;     ...
;         for (int k = 0; k < 3; ++k) {
;             if (tl - k >= 0) { const bf16_t* r = PROJ + (size_t)(tok - k) * NPJ; float gc[8], xc[8]; unpack8(*(const u32x4*)(r + PJ_GC + ch), gc); unpack8(*(const u32x4*)(r + PJ_XC + ch), xc);
; #pragma unroll
;                 for (int j = 0; j < 8; ++j) z[k][j] = gc[j] * xc[j];
;             } else if (pr) {
; #pragma unroll
;                 for (int j = 0; j < 8; ++j) z[k][j] = 0.f;
;             } else { const float* cb = a->in[6] + (size_t)((l * 32 + sb) * 2 + (tl - k + 2)) * 512 + ch; const f32x4 c0 = *(const f32x4*)cb, c1 = *(const f32x4*)(cb + 4);
; #pragma unroll
;                 for (int j = 0; j < 4; ++j) { z[k][j] = c0[j]; z[k][4 + j] = c1[j]; } }
;         }
;         float gb[8]; unpack8(*(const u32x4*)(PROJ + (size_t)tok * NPJ + PJ_GB + ch), gb);
;         float y[8], ss = 0.f;
; #pragma unroll
;         for (int j = 0; j < 8; ++j) { y[j] = gb[j] * (w0[j] * z[2][j] + w1[j] * z[1][j] + w2[j] * z[0][j]); ss += y[j] * y[j]; }
;         const float rs = rsqrtf(wave_sum(ss) * (1.0f / 512.0f) + EPS);
;         u32x4 w; w.x = pk2(y[0] * rs * og[0], y[1] * rs * og[1]); w.y = pk2(y[2] * rs * og[2], y[3] * rs * og[3]); w.z = pk2(y[4] * rs * og[4], y[5] * rs * og[5]); w.w = pk2(y[6] * rs * og[6], y[7] * rs * og[7]);
;         *(u32x4*)(YC + (size_t)tok * D + 1536 + ch) = w;
.LBB0_377:
	s_andn2_b64 vcc, exec, s[2:3]
	s_cbranch_vccnz .LBB0_379
	s_add_i32 s0, s15, -2
	s_mul_hi_i32 s1, s0, 0x1600
	s_mulk_i32 s0, 0x1600
	v_readlane_b32 s2, v255, 25
	v_readlane_b32 s3, v255, 26
	s_add_u32 s0, s2, s0
	s_addc_u32 s1, s3, s1
	s_waitcnt vmcnt(1)
	v_lshl_add_u64 v[38:39], s[0:1], 0, v[160:161]
	v_add_co_u32_e32 v38, vcc, s86, v38
	s_nop 0
	v_addc_co_u32_e32 v39, vcc, 0, v39, vcc
	s_waitcnt vmcnt(0)
	v_mov_b32_e32 v26, v76
	v_mov_b32_e32 v27, v77
	v_mov_b32_e32 v28, v78
	v_mov_b32_e32 v29, v79
	v_lshlrev_b32_e32 v38, 16, v26
	v_and_b32_e32 v39, 0xffff0000, v26
	v_lshlrev_b32_e32 v26, 16, v27
	s_waitcnt vmcnt(0)
	v_mov_b32_e32 v42, v80
	v_mov_b32_e32 v43, v81
	v_mov_b32_e32 v44, v82
	v_mov_b32_e32 v45, v83
	v_lshlrev_b32_e32 v40, 16, v42
	v_and_b32_e32 v41, 0xffff0000, v42
	v_pk_mul_f32 v[38:39], v[38:39], v[40:41]
	v_and_b32_e32 v27, 0xffff0000, v27
	v_lshlrev_b32_e32 v40, 16, v43
	v_and_b32_e32 v41, 0xffff0000, v43
	v_pk_mul_f32 v[40:41], v[26:27], v[40:41]
	v_lshlrev_b32_e32 v26, 16, v28
	v_and_b32_e32 v27, 0xffff0000, v28
	v_lshlrev_b32_e32 v42, 16, v44
	v_and_b32_e32 v43, 0xffff0000, v44
	v_pk_mul_f32 v[42:43], v[26:27], v[42:43]
	v_lshlrev_b32_e32 v26, 16, v29
	v_and_b32_e32 v27, 0xffff0000, v29
	v_lshlrev_b32_e32 v28, 16, v45
	v_and_b32_e32 v29, 0xffff0000, v45
	v_pk_mul_f32 v[44:45], v[26:27], v[28:29]
.LBB0_379:
	s_waitcnt vmcnt(1)
	v_lshlrev_b32_e32 v26, 16, v34
	v_and_b32_e32 v27, 0xffff0000, v34
	s_waitcnt vmcnt(0)
	v_lshlrev_b32_e32 v28, 16, v30
	v_and_b32_e32 v29, 0xffff0000, v30
	v_pk_mul_f32 v[26:27], v[26:27], v[28:29]
	v_lshlrev_b32_e32 v28, 16, v35
	v_and_b32_e32 v29, 0xffff0000, v35
	v_lshlrev_b32_e32 v30, 16, v31
	v_and_b32_e32 v31, 0xffff0000, v31
	v_pk_mul_f32 v[28:29], v[28:29], v[30:31]
	v_lshlrev_b32_e32 v30, 16, v36
	v_and_b32_e32 v31, 0xffff0000, v36
	v_lshlrev_b32_e32 v34, 16, v32
	v_and_b32_e32 v35, 0xffff0000, v32
	v_pk_mul_f32 v[30:31], v[30:31], v[34:35]
	v_lshlrev_b32_e32 v34, 16, v37
	v_and_b32_e32 v35, 0xffff0000, v37
	v_lshlrev_b32_e32 v32, 16, v33
	v_and_b32_e32 v33, 0xffff0000, v33
	v_pk_mul_f32 v[32:33], v[34:35], v[32:33]
	v_pk_mul_f32 v[44:45], v[10:11], v[44:45]
	v_pk_mul_f32 v[40:41], v[18:19], v[40:41]
	v_pk_fma_f32 v[24:25], v[50:51], v[24:25], v[44:45]
	v_pk_fma_f32 v[16:17], v[56:57], v[16:17], v[40:41]
	v_pk_fma_f32 v[24:25], v[48:49], v[32:33], v[24:25]
	v_pk_fma_f32 v[16:17], v[54:55], v[28:29], v[16:17]
	s_and_b64 s[0:1], s[10:11], exec
	s_cselect_b32 s0, 0x3ffe, 62
	s_cmp_lt_u32 s18, s0
	s_waitcnt vmcnt(0)
	v_mov_b32_e32 v34, v84
	v_mov_b32_e32 v35, v85
	v_mov_b32_e32 v36, v86
	v_mov_b32_e32 v37, v87
	v_lshlrev_b32_e32 v72, 16, v37
	v_and_b32_e32 v73, 0xffff0000, v37
	v_pk_mul_f32 v[24:25], v[24:25], v[72:73]
	v_lshlrev_b32_e32 v72, 16, v36
	v_and_b32_e32 v73, 0xffff0000, v36
	v_pk_mul_f32 v[36:37], v[20:21], v[42:43]
	v_lshlrev_b32_e32 v42, 16, v35
	v_and_b32_e32 v43, 0xffff0000, v35
	v_pk_mul_f32 v[16:17], v[16:17], v[42:43]
	v_lshlrev_b32_e32 v42, 16, v34
	v_and_b32_e32 v43, 0xffff0000, v34
	v_pk_mul_f32 v[34:35], v[12:13], v[38:39]
	v_pk_fma_f32 v[22:23], v[8:9], v[22:23], v[36:37]
	v_pk_fma_f32 v[14:15], v[60:61], v[14:15], v[34:35]
	v_pk_fma_f32 v[22:23], v[52:53], v[30:31], v[22:23]
	v_pk_fma_f32 v[14:15], v[58:59], v[26:27], v[14:15]
	v_pk_mul_f32 v[40:41], v[16:17], v[16:17]
	v_pk_mul_f32 v[14:15], v[14:15], v[42:43]
	v_pk_mul_f32 v[22:23], v[22:23], v[72:73]
	v_pk_mul_f32 v[34:35], v[14:15], v[14:15]
	v_pk_mul_f32 v[36:37], v[22:23], v[22:23]
	v_add_f32_e32 v34, v34, v35
	v_add_f32_e32 v34, v40, v34
	v_add_f32_e32 v34, v41, v34
	v_add_f32_e32 v34, v36, v34
	v_pk_mul_f32 v[44:45], v[24:25], v[24:25]
	v_add_f32_e32 v34, v37, v34
	v_add_f32_e32 v34, v44, v34
	v_add_f32_e32 v34, v45, v34
	ds_bpermute_b32 v35, v47, v34
	s_waitcnt lgkmcnt(0)
	v_add_f32_e32 v34, v34, v35
	ds_bpermute_b32 v35, v66, v34
	s_waitcnt lgkmcnt(0)
	v_add_f32_e32 v34, v34, v35
	ds_bpermute_b32 v35, v67, v34
	s_waitcnt lgkmcnt(0)
	v_add_f32_e32 v34, v34, v35
	ds_bpermute_b32 v35, v68, v34
	s_waitcnt lgkmcnt(0)
	v_add_f32_e32 v34, v34, v35
	ds_bpermute_b32 v35, v69, v34
	s_waitcnt lgkmcnt(0)
	v_add_f32_e32 v34, v34, v35
	ds_bpermute_b32 v35, v70, v34
	s_waitcnt lgkmcnt(0)
	v_add_f32_e32 v34, v34, v35
	v_fmamk_f32 v34, v34, 0x3b000000, v162
	v_cmp_gt_f32_e32 vcc, s91, v34
	v_mul_f32_e32 v35, 0x4b800000, v34
	s_nop 0
	v_cndmask_b32_e32 v34, v34, v35, vcc
	v_rsq_f32_e32 v34, v34
	s_nop 0
	v_mul_f32_e32 v35, 0x45800000, v34
	v_cndmask_b32_e32 v34, v34, v35, vcc
	v_pk_mul_f32 v[14:15], v[14:15], v[34:35] op_sel_hi:[1,0]
	v_pk_mul_f32 v[16:17], v[16:17], v[34:35] op_sel_hi:[1,0]
	v_pk_mul_f32 v[14:15], v[0:1], v[14:15]
	v_pk_mul_f32 v[16:17], v[2:3], v[16:17]
	v_cvt_pk_bf16_f32 v14, v14, v15
	v_cvt_pk_bf16_f32 v15, v16, v17
	v_pk_mul_f32 v[16:17], v[22:23], v[34:35] op_sel_hi:[1,0]
	v_pk_mul_f32 v[22:23], v[24:25], v[34:35] op_sel_hi:[1,0]
	v_pk_mul_f32 v[16:17], v[4:5], v[16:17]
	v_pk_mul_f32 v[22:23], v[6:7], v[22:23]
	v_cvt_pk_bf16_f32 v16, v16, v17
	v_cvt_pk_bf16_f32 v17, v22, v23
	global_store_dwordx4 v[62:63], v[14:17], off
	s_cbranch_scc1 .LBB0_366
	s_mov_b64 s[2:3], -1
	s_and_b64 vcc, exec, s[8:9]
	s_cbranch_vccz .LBB0_382
	s_add_i32 s0, s13, s17
	s_add_i32 s0, s0, s19
	s_mov_b64 s[2:3], 0

; __device__ __forceinline__ void unpack8(u32x4 w, float* f) { f[0] = bflo(w.x); f[1] = bfhi(w.x); f[2] = bflo(w.y); f[3] = bfhi(w.y); f[4] = bflo(w.z); f[5] = bfhi(w.z); f[6] = bflo(w.w); f[7] = bfhi(w.w); }
; __device__ __forceinline__ void rownorm_phase(const XBuf xin, const float* mod_shift, const float* mod_scale, bf16_t* XN, int lane, int gw, int NGW) {
;     for (int row0 = gw * 2; row0 < T; row0 += NGW * 2) {
;         const int bi = batch_of(row0);
;         float v[2][4][8]; float ss0 = 0.f, ss1 = 0.f;
; #pragma unroll
;         for (int j = 0; j < 4; ++j) { xload8(xin, row0, 8 * lane + 512 * j, v[0][j]); xload8(xin, row0 + 1, 8 * lane + 512 * j, v[1][j]); }
; #pragma unroll
;         for (int j = 0; j < 4; ++j)
; #pragma unroll
;             for (int k = 0; k < 8; ++k) { ss0 += v[0][j][k] * v[0][j][k]; ss1 += v[1][j][k] * v[1][j][k]; }
;         const float rs0 = rsqrtf(wave_sum(ss0) * (1.0f / D) + EPS), rs1 = rsqrtf(wave_sum(ss1) * (1.0f / D) + EPS);
;         const float* sh = mod_shift + (size_t)bi * NMOD; const float* sc = mod_scale + (size_t)bi * NMOD;
; #pragma unroll
;         for (int j = 0; j < 4; ++j) { const int c = 8 * lane + 512 * j;
;             const f32x4 s0 = 1.0f + *(const f32x4*)(sc + c), s1 = 1.0f + *(const f32x4*)(sc + c + 4), h0 = *(const f32x4*)(sh + c), h1 = *(const f32x4*)(sh + c + 4);
.LBB0_796:
	s_waitcnt vmcnt(0)
	v_readlane_b32 s0, v254, 31
	v_readlane_b32 s1, v254, 32
	s_nop 1
	s_cmp_lg_u64 s[0:1], 0
	s_cbranch_scc0 .Lrn0_skip
	v_lshlrev_b32_e32 v4, 16, v0
	v_and_b32_e32 v5, 0xffff0000, v0
	v_lshlrev_b32_e32 v6, 16, v1
	v_and_b32_e32 v7, 0xffff0000, v1
	v_lshlrev_b32_e32 v0, 16, v2
	v_and_b32_e32 v1, 0xffff0000, v2
	v_lshlrev_b32_e32 v2, 16, v3
	v_and_b32_e32 v3, 0xffff0000, v3
	v_lshlrev_b32_e32 v12, 16, v8
	v_and_b32_e32 v13, 0xffff0000, v8
	v_lshlrev_b32_e32 v14, 16, v9
	v_and_b32_e32 v15, 0xffff0000, v9
	v_lshlrev_b32_e32 v8, 16, v10
	v_and_b32_e32 v9, 0xffff0000, v10
	v_lshlrev_b32_e32 v10, 16, v11
	v_and_b32_e32 v11, 0xffff0000, v11
	v_lshlrev_b32_e32 v20, 16, v16
	v_and_b32_e32 v21, 0xffff0000, v16
	v_lshlrev_b32_e32 v22, 16, v17
	v_and_b32_e32 v23, 0xffff0000, v17
	v_lshlrev_b32_e32 v16, 16, v18
	v_and_b32_e32 v17, 0xffff0000, v18
	v_lshlrev_b32_e32 v18, 16, v19
	v_and_b32_e32 v19, 0xffff0000, v19
	v_lshlrev_b32_e32 v28, 16, v24
	v_and_b32_e32 v29, 0xffff0000, v24
	v_lshlrev_b32_e32 v30, 16, v25
	v_and_b32_e32 v31, 0xffff0000, v25
	v_lshlrev_b32_e32 v24, 16, v26
	v_and_b32_e32 v25, 0xffff0000, v26
	v_lshlrev_b32_e32 v26, 16, v27
	v_and_b32_e32 v27, 0xffff0000, v27
	v_lshlrev_b32_e32 v36, 16, v32
	v_and_b32_e32 v37, 0xffff0000, v32
	v_lshlrev_b32_e32 v38, 16, v33
	v_and_b32_e32 v39, 0xffff0000, v33
	v_lshlrev_b32_e32 v32, 16, v34
	v_and_b32_e32 v33, 0xffff0000, v34
	v_lshlrev_b32_e32 v34, 16, v35
	v_and_b32_e32 v35, 0xffff0000, v35
	v_lshlrev_b32_e32 v44, 16, v40
	v_and_b32_e32 v45, 0xffff0000, v40
	v_lshlrev_b32_e32 v46, 16, v41
	v_and_b32_e32 v47, 0xffff0000, v41
	v_lshlrev_b32_e32 v40, 16, v42
	v_and_b32_e32 v41, 0xffff0000, v42
	v_lshlrev_b32_e32 v42, 16, v43
	v_and_b32_e32 v43, 0xffff0000, v43
	v_lshlrev_b32_e32 v48, 16, v52
	v_and_b32_e32 v49, 0xffff0000, v52
	v_lshlrev_b32_e32 v50, 16, v53
	v_and_b32_e32 v51, 0xffff0000, v53
	v_lshlrev_b32_e32 v52, 16, v54
	v_and_b32_e32 v53, 0xffff0000, v54
	v_lshlrev_b32_e32 v54, 16, v55
	v_and_b32_e32 v55, 0xffff0000, v55
	v_lshlrev_b32_e32 v56, 16, v60
	v_and_b32_e32 v57, 0xffff0000, v60
	v_lshlrev_b32_e32 v58, 16, v61
	v_and_b32_e32 v59, 0xffff0000, v61
	v_lshlrev_b32_e32 v60, 16, v62
	v_and_b32_e32 v61, 0xffff0000, v62
	v_lshlrev_b32_e32 v62, 16, v63
	v_and_b32_e32 v63, 0xffff0000, v63
.Lrn0_skip:
	v_mov_b32_e32 v90, v12
	v_mov_b32_e32 v91, v4
	v_pk_mul_f32 v[90:91], v[90:91], v[90:91]
	v_mov_b32_e32 v92, v13
	v_mov_b32_e32 v93, v5
	v_pk_fma_f32 v[90:91], v[92:93], v[92:93], v[90:91]
	v_mov_b32_e32 v92, v14
	v_mov_b32_e32 v93, v6
	v_pk_fma_f32 v[90:91], v[92:93], v[92:93], v[90:91]
	v_mov_b32_e32 v92, v15
	v_mov_b32_e32 v93, v7
	v_pk_fma_f32 v[90:91], v[92:93], v[92:93], v[90:91]
	v_mov_b32_e32 v92, v8
	v_mov_b32_e32 v93, v0
	v_pk_fma_f32 v[90:91], v[92:93], v[92:93], v[90:91]
	v_mov_b32_e32 v92, v9
	v_mov_b32_e32 v93, v1
	v_pk_fma_f32 v[90:91], v[92:93], v[92:93], v[90:91]
	v_mov_b32_e32 v92, v10
	v_mov_b32_e32 v93, v2
	v_pk_fma_f32 v[90:91], v[92:93], v[92:93], v[90:91]
	v_mov_b32_e32 v92, v11
	v_mov_b32_e32 v93, v3
	v_pk_fma_f32 v[90:91], v[92:93], v[92:93], v[90:91]
	v_mov_b32_e32 v92, v28
	v_mov_b32_e32 v93, v20
	v_pk_fma_f32 v[90:91], v[92:93], v[92:93], v[90:91]
	v_mov_b32_e32 v92, v29
	v_mov_b32_e32 v93, v21
	v_pk_fma_f32 v[90:91], v[92:93], v[92:93], v[90:91]
	v_mov_b32_e32 v92, v30
	v_mov_b32_e32 v93, v22
	v_pk_fma_f32 v[90:91], v[92:93], v[92:93], v[90:91]
	v_mov_b32_e32 v92, v31
	v_mov_b32_e32 v93, v23
	v_pk_fma_f32 v[90:91], v[92:93], v[92:93], v[90:91]
	v_mov_b32_e32 v92, v24
	v_mov_b32_e32 v93, v16
	v_pk_fma_f32 v[90:91], v[92:93], v[92:93], v[90:91]
	v_mov_b32_e32 v92, v25
	v_mov_b32_e32 v93, v17
	v_pk_fma_f32 v[90:91], v[92:93], v[92:93], v[90:91]
	v_mov_b32_e32 v92, v26
	v_mov_b32_e32 v93, v18
	s_add_i32 s0, s4, 0xffff8000
	v_pk_fma_f32 v[90:91], v[92:93], v[92:93], v[90:91]
	v_mov_b32_e32 v92, v27
	v_mov_b32_e32 v93, v19
	s_lshr_b32 s0, s0, 6
	v_pk_fma_f32 v[90:91], v[92:93], v[92:93], v[90:91]
	v_mov_b32_e32 v92, v44
	v_mov_b32_e32 v93, v36
	s_add_i32 s0, s0, 2
	s_ashr_i32 s1, s4, 14
	v_pk_fma_f32 v[90:91], v[92:93], v[92:93], v[90:91]
	v_mov_b32_e32 v92, v45
	v_mov_b32_e32 v93, v37
	s_cmp_lt_i32 s4, 0x8000
	v_pk_fma_f32 v[90:91], v[92:93], v[92:93], v[90:91]
	v_mov_b32_e32 v92, v46
	v_mov_b32_e32 v93, v38
	v_pk_fma_f32 v[90:91], v[92:93], v[92:93], v[90:91]
	v_mov_b32_e32 v92, v47
	v_mov_b32_e32 v93, v39
	s_cselect_b32 s0, s1, s0
	v_pk_fma_f32 v[90:91], v[92:93], v[92:93], v[90:91]
	v_mov_b32_e32 v92, v40
	v_mov_b32_e32 v93, v32
	s_mul_hi_i32 s1, s0, 0xc000
	s_mul_i32 s0, s0, 0xc000
	v_readlane_b32 s2, v254, 22
	v_pk_fma_f32 v[90:91], v[92:93], v[92:93], v[90:91]
	v_mov_b32_e32 v92, v41
	v_mov_b32_e32 v93, v33
	s_add_u32 s12, s2, s0
	v_readlane_b32 s2, v254, 23
	v_pk_fma_f32 v[90:91], v[92:93], v[92:93], v[90:91]
	v_mov_b32_e32 v92, v42
	v_mov_b32_e32 v93, v34
	s_addc_u32 s13, s2, s1
	v_pk_fma_f32 v[90:91], v[92:93], v[92:93], v[90:91]
	v_mov_b32_e32 v92, v43
	v_mov_b32_e32 v93, v35
	s_add_u32 s14, s16, s0
	v_pk_fma_f32 v[90:91], v[92:93], v[92:93], v[90:91]
	v_mov_b32_e32 v92, v56
	v_mov_b32_e32 v93, v48
	s_addc_u32 s15, s17, s1
	v_pk_fma_f32 v[98:99], v[92:93], v[92:93], v[90:91]
	global_load_dwordx4 v[90:93], v86, s[14:15] offset:16
	global_load_dwordx4 v[94:97], v86, s[14:15]
	v_mov_b32_e32 v100, v57
	v_mov_b32_e32 v101, v49
	v_pk_fma_f32 v[110:111], v[100:101], v[100:101], v[98:99]
	global_load_dwordx4 v[98:101], v86, s[12:13] offset:16
	global_load_dwordx4 v[102:105], v86, s[12:13]
	v_mov_b32_e32 v112, v58
	v_mov_b32_e32 v113, v50
	v_pk_mul_f32 v[106:107], v[52:53], v[52:53]
	v_pk_mul_f32 v[108:109], v[60:61], v[60:61]
	v_pk_fma_f32 v[110:111], v[112:113], v[112:113], v[110:111]
	v_mov_b32_e32 v112, v59
	v_mov_b32_e32 v113, v51
	v_pk_fma_f32 v[110:111], v[112:113], v[112:113], v[110:111]
	v_mov_b32_e32 v112, v108
	v_mov_b32_e32 v113, v106
	v_pk_add_f32 v[110:111], v[112:113], v[110:111]
	v_pk_mul_f32 v[112:113], v[54:55], v[54:55]
	v_pk_mul_f32 v[114:115], v[62:63], v[62:63]
	v_mov_b32_e32 v106, v109
	v_pk_add_f32 v[106:107], v[106:107], v[110:111]
	v_mov_b32_e32 v108, v114
	v_mov_b32_e32 v109, v112
	v_pk_add_f32 v[106:107], v[108:109], v[106:107]
	v_mov_b32_e32 v112, v115
	v_pk_add_f32 v[106:107], v[112:113], v[106:107]
	ds_bpermute_b32 v109, v80, v107
	ds_bpermute_b32 v108, v80, v106
	s_mov_b32 s0, 0x3a000000
	s_add_i32 s4, s4, s6
	s_add_u32 s10, s10, s6
	s_addc_u32 s11, s11, s7
	s_waitcnt lgkmcnt(0)
; __device__ __forceinline__ unsigned pk2(float lo, float hi) { const f32x2 v = {lo, hi}; return __builtin_bit_cast(unsigned, __builtin_convertvector(v, bf16x2_t)); }
; __device__ __forceinline__ void rownorm_phase(const XBuf xin, const float* mod_shift, const float* mod_scale, bf16_t* XN, int lane, int gw, int NGW) {
;     ...
;         const float rs0 = rsqrtf(wave_sum(ss0) * (1.0f / D) + EPS), rs1 = rsqrtf(wave_sum(ss1) * (1.0f / D) + EPS);
;         const float* sh = mod_shift + (size_t)bi * NMOD; const float* sc = mod_scale + (size_t)bi * NMOD;
; #pragma unroll
;         for (int j = 0; j < 4; ++j) { const int c = 8 * lane + 512 * j;
;             const f32x4 s0 = 1.0f + *(const f32x4*)(sc + c), s1 = 1.0f + *(const f32x4*)(sc + c + 4), h0 = *(const f32x4*)(sh + c), h1 = *(const f32x4*)(sh + c + 4);
;             u32x4 w0, w1;
;             w0.x = pk2(v[0][j][0] * rs0 * s0[0] + h0[0], v[0][j][1] * rs0 * s0[1] + h0[1]); w0.y = pk2(v[0][j][2] * rs0 * s0[2] + h0[2], v[0][j][3] * rs0 * s0[3] + h0[3]);
;             w0.z = pk2(v[0][j][4] * rs0 * s1[0] + h1[0], v[0][j][5] * rs0 * s1[1] + h1[1]); w0.w = pk2(v[0][j][6] * rs0 * s1[2] + h1[2], v[0][j][7] * rs0 * s1[3] + h1[3]);
;             w1.x = pk2(v[1][j][0] * rs1 * s0[0] + h0[0], v[1][j][1] * rs1 * s0[1] + h0[1]); w1.y = pk2(v[1][j][2] * rs1 * s0[2] + h0[2], v[1][j][3] * rs1 * s0[3] + h0[3]);
;             w1.z = pk2(v[1][j][4] * rs1 * s1[0] + h1[0], v[1][j][5] * rs1 * s1[1] + h1[1]); w1.w = pk2(v[1][j][6] * rs1 * s1[2] + h1[2], v[1][j][7] * rs1 * s1[3] + h1[3]);
;             *(u32x4*)(XN + (size_t)row0 * D + c) = w0; *(u32x4*)(XN + (size_t)(row0 + 1) * D + c) = w1; }
	v_pk_add_f32 v[106:107], v[106:107], v[108:109]
	ds_bpermute_b32 v109, v81, v107
	ds_bpermute_b32 v108, v81, v106
	s_cmp_gt_i32 s4, 0x87ff
	s_waitcnt lgkmcnt(0)
	v_pk_add_f32 v[106:107], v[106:107], v[108:109]
	ds_bpermute_b32 v109, v82, v107
	ds_bpermute_b32 v108, v82, v106
	s_waitcnt lgkmcnt(0)
	v_pk_add_f32 v[106:107], v[106:107], v[108:109]
	ds_bpermute_b32 v109, v83, v107
	ds_bpermute_b32 v108, v83, v106
	s_waitcnt lgkmcnt(0)
	v_pk_add_f32 v[106:107], v[106:107], v[108:109]
	ds_bpermute_b32 v109, v84, v107
	ds_bpermute_b32 v108, v84, v106
	s_waitcnt lgkmcnt(0)
	v_pk_add_f32 v[106:107], v[106:107], v[108:109]
	ds_bpermute_b32 v109, v85, v107
	ds_bpermute_b32 v108, v85, v106
	s_waitcnt lgkmcnt(0)
	v_pk_add_f32 v[106:107], v[106:107], v[108:109]
	s_nop 0
	v_pk_fma_f32 v[106:107], v[106:107], s[0:1], v[162:163] op_sel_hi:[1,0,0]
	s_waitcnt vmcnt(3)
	v_pk_add_f32 v[90:91], v[90:91], 1.0 op_sel_hi:[1,0]
	v_mul_f32_e32 v89, 0x4b800000, v107
	v_cmp_gt_f32_e32 vcc, s91, v107
	v_cmp_gt_f32_e64 s[0:1], s91, v106
	s_waitcnt vmcnt(2)
	v_pk_add_f32 v[96:97], v[96:97], 1.0 op_sel_hi:[1,0]
	v_cndmask_b32_e32 v89, v107, v89, vcc
	v_rsq_f32_e32 v89, v89
	v_mul_f32_e32 v107, 0x4b800000, v106
	v_cndmask_b32_e64 v106, v106, v107, s[0:1]
	v_rsq_f32_e32 v107, v106
	v_mul_f32_e32 v106, 0x45800000, v89
	v_cndmask_b32_e32 v106, v89, v106, vcc
	v_pk_add_f32 v[94:95], v[94:95], 1.0 op_sel_hi:[1,0]
	v_pk_mul_f32 v[4:5], v[4:5], v[106:107] op_sel_hi:[1,0]
	v_pk_mul_f32 v[6:7], v[6:7], v[106:107] op_sel_hi:[1,0]
	v_pk_mul_f32 v[0:1], v[0:1], v[106:107] op_sel_hi:[1,0]
	s_waitcnt vmcnt(0)
	v_pk_fma_f32 v[4:5], v[94:95], v[4:5], v[102:103]
	v_pk_fma_f32 v[6:7], v[96:97], v[6:7], v[104:105]
	v_pk_fma_f32 v[0:1], v[90:91], v[0:1], v[98:99]
	v_mul_f32_e32 v89, 0x45800000, v107
	v_pk_add_f32 v[92:93], v[92:93], 1.0 op_sel_hi:[1,0]
	v_cvt_pk_bf16_f32 v4, v4, v5
	v_cvt_pk_bf16_f32 v5, v6, v7
	v_cvt_pk_bf16_f32 v6, v0, v1
	v_pk_mul_f32 v[0:1], v[2:3], v[106:107] op_sel_hi:[1,0]
	v_cndmask_b32_e64 v108, v107, v89, s[0:1]
	v_pk_fma_f32 v[0:1], v[92:93], v[0:1], v[100:101]
	v_pk_mul_f32 v[2:3], v[14:15], v[108:109] op_sel_hi:[1,0]
	v_cvt_pk_bf16_f32 v7, v0, v1
	v_pk_mul_f32 v[0:1], v[12:13], v[108:109] op_sel_hi:[1,0]
	v_pk_fma_f32 v[2:3], v[96:97], v[2:3], v[104:105]
	v_pk_fma_f32 v[0:1], v[94:95], v[0:1], v[102:103]
	s_movk_i32 s0, 0xf000
	v_cvt_pk_bf16_f32 v0, v0, v1
	v_cvt_pk_bf16_f32 v1, v2, v3
	v_pk_mul_f32 v[2:3], v[8:9], v[108:109] op_sel_hi:[1,0]
	v_pk_mul_f32 v[8:9], v[10:11], v[108:109] op_sel_hi:[1,0]
	v_pk_fma_f32 v[2:3], v[90:91], v[2:3], v[98:99]
	v_add_co_u32_e32 v90, vcc, s0, v78
	v_pk_fma_f32 v[8:9], v[92:93], v[8:9], v[100:101]
	s_nop 0
	v_addc_co_u32_e32 v91, vcc, -1, v79, vcc
	v_cvt_pk_bf16_f32 v2, v2, v3
	v_cvt_pk_bf16_f32 v3, v8, v9
	global_store_dwordx4 v[90:91], v[4:7], off offset:-3072
	global_store_dwordx4 v[78:79], v[0:3], off offset:-3072
	global_load_dwordx4 v[0:3], v86, s[14:15] offset:2048
	s_nop 0
	global_load_dwordx4 v[4:7], v86, s[14:15] offset:2064
	global_load_dwordx4 v[8:11], v86, s[12:13] offset:2048
	global_load_dwordx4 v[12:15], v86, s[12:13] offset:2064
	s_waitcnt vmcnt(3)
	v_pk_add_f32 v[92:93], v[2:3], 1.0 op_sel_hi:[1,0]
	v_pk_add_f32 v[94:95], v[0:1], 1.0 op_sel_hi:[1,0]
	v_pk_mul_f32 v[0:1], v[20:21], v[106:107] op_sel_hi:[1,0]
	v_pk_mul_f32 v[2:3], v[22:23], v[106:107] op_sel_hi:[1,0]
	s_waitcnt vmcnt(1)
	v_pk_fma_f32 v[0:1], v[0:1], v[94:95], v[8:9]
	v_pk_fma_f32 v[2:3], v[2:3], v[92:93], v[10:11]
	v_pk_add_f32 v[96:97], v[6:7], 1.0 op_sel_hi:[1,0]
	v_pk_add_f32 v[6:7], v[4:5], 1.0 op_sel_hi:[1,0]
	v_cvt_pk_bf16_f32 v0, v0, v1
	v_cvt_pk_bf16_f32 v1, v2, v3
	v_pk_mul_f32 v[2:3], v[16:17], v[106:107] op_sel_hi:[1,0]
	v_pk_mul_f32 v[4:5], v[18:19], v[106:107] op_sel_hi:[1,0]
	s_waitcnt vmcnt(0)
	v_pk_fma_f32 v[2:3], v[2:3], v[6:7], v[12:13]
	v_pk_fma_f32 v[4:5], v[4:5], v[96:97], v[14:15]
	v_cvt_pk_bf16_f32 v2, v2, v3
	v_cvt_pk_bf16_f32 v3, v4, v5
	v_pk_mul_f32 v[4:5], v[28:29], v[108:109] op_sel_hi:[1,0]
	v_pk_mul_f32 v[16:17], v[36:37], v[106:107] op_sel_hi:[1,0]
	v_pk_fma_f32 v[4:5], v[94:95], v[4:5], v[8:9]
	v_pk_mul_f32 v[8:9], v[30:31], v[108:109] op_sel_hi:[1,0]
	v_cvt_pk_bf16_f32 v4, v4, v5
	v_pk_fma_f32 v[8:9], v[92:93], v[8:9], v[10:11]
	v_pk_mul_f32 v[18:19], v[38:39], v[106:107] op_sel_hi:[1,0]
	v_cvt_pk_bf16_f32 v5, v8, v9
	v_pk_mul_f32 v[8:9], v[24:25], v[108:109] op_sel_hi:[1,0]
	v_pk_mul_f32 v[20:21], v[32:33], v[106:107] op_sel_hi:[1,0]
	v_pk_fma_f32 v[6:7], v[6:7], v[8:9], v[12:13]
	v_pk_mul_f32 v[8:9], v[26:27], v[108:109] op_sel_hi:[1,0]
	v_cvt_pk_bf16_f32 v6, v6, v7
	v_pk_fma_f32 v[8:9], v[96:97], v[8:9], v[14:15]
	v_pk_mul_f32 v[22:23], v[34:35], v[106:107] op_sel_hi:[1,0]
	v_cvt_pk_bf16_f32 v7, v8, v9
	global_store_dwordx4 v[90:91], v[0:3], off offset:-2048
	global_store_dwordx4 v[78:79], v[4:7], off offset:-2048
	global_load_dwordx4 v[0:3], v87, s[14:15]
	s_nop 0
	global_load_dwordx4 v[4:7], v87, s[14:15] offset:16
	global_load_dwordx4 v[8:11], v87, s[12:13]
	global_load_dwordx4 v[12:15], v87, s[12:13] offset:16
	v_pk_mul_f32 v[24:25], v[44:45], v[108:109] op_sel_hi:[1,0]
	v_pk_mul_f32 v[26:27], v[46:47], v[108:109] op_sel_hi:[1,0]
	v_pk_mul_f32 v[28:29], v[40:41], v[108:109] op_sel_hi:[1,0]
	v_pk_mul_f32 v[30:31], v[42:43], v[108:109] op_sel_hi:[1,0]
	s_waitcnt vmcnt(3)
	v_pk_add_f32 v[2:3], v[2:3], 1.0 op_sel_hi:[1,0]
	v_pk_add_f32 v[0:1], v[0:1], 1.0 op_sel_hi:[1,0]
	s_waitcnt vmcnt(2)
	v_pk_add_f32 v[6:7], v[6:7], 1.0 op_sel_hi:[1,0]
	v_pk_add_f32 v[4:5], v[4:5], 1.0 op_sel_hi:[1,0]
	s_waitcnt vmcnt(1)
	v_pk_fma_f32 v[16:17], v[16:17], v[0:1], v[8:9]
	v_pk_fma_f32 v[18:19], v[18:19], v[2:3], v[10:11]
	s_waitcnt vmcnt(0)
; __device__ __forceinline__ unsigned pk2(float lo, float hi) { const f32x2 v = {lo, hi}; return __builtin_bit_cast(unsigned, __builtin_convertvector(v, bf16x2_t)); }
; __device__ __forceinline__ void unpack8(u32x4 w, float* f) { f[0] = bflo(w.x); f[1] = bfhi(w.x); f[2] = bflo(w.y); f[3] = bfhi(w.y); f[4] = bflo(w.z); f[5] = bfhi(w.z); f[6] = bflo(w.w); f[7] = bfhi(w.w); }
; __device__ __forceinline__ const unsigned char* xrow(const XBuf& b, int row) { return (row < b.split ? b.p0 : b.p1) + (size_t)row * (b.f32 ? 8192 : 4096); }
; __device__ __forceinline__ void xload8(const XBuf& b, int row, int col, float* v) {
;     const unsigned char* r = xrow(b, row);
;     if (b.f32) { const f32x4 a0 = *(const f32x4*)(r + (size_t)col * 4), a1 = *(const f32x4*)(r + (size_t)col * 4 + 16);
; #pragma unroll
;         for (int j = 0; j < 4; ++j) { v[j] = a0[j]; v[4 + j] = a1[j]; } }
;     else unpack8(*(const u32x4*)(r + (size_t)col * 2), v);
; __device__ __forceinline__ void rownorm_phase(const XBuf xin, const float* mod_shift, const float* mod_scale, bf16_t* XN, int lane, int gw, int NGW) {
;     ...
;         for (int j = 0; j < 4; ++j) { const int c = 8 * lane + 512 * j;
;             const f32x4 s0 = 1.0f + *(const f32x4*)(sc + c), s1 = 1.0f + *(const f32x4*)(sc + c + 4), h0 = *(const f32x4*)(sh + c), h1 = *(const f32x4*)(sh + c + 4);
;             u32x4 w0, w1;
;             w0.x = pk2(v[0][j][0] * rs0 * s0[0] + h0[0], v[0][j][1] * rs0 * s0[1] + h0[1]); w0.y = pk2(v[0][j][2] * rs0 * s0[2] + h0[2], v[0][j][3] * rs0 * s0[3] + h0[3]);
;             w0.z = pk2(v[0][j][4] * rs0 * s1[0] + h1[0], v[0][j][5] * rs0 * s1[1] + h1[1]); w0.w = pk2(v[0][j][6] * rs0 * s1[2] + h1[2], v[0][j][7] * rs0 * s1[3] + h1[3]);
;             w1.x = pk2(v[1][j][0] * rs1 * s0[0] + h0[0], v[1][j][1] * rs1 * s0[1] + h0[1]); w1.y = pk2(v[1][j][2] * rs1 * s0[2] + h0[2], v[1][j][3] * rs1 * s0[3] + h0[3]);
;             w1.z = pk2(v[1][j][4] * rs1 * s1[0] + h1[0], v[1][j][5] * rs1 * s1[1] + h1[1]); w1.w = pk2(v[1][j][6] * rs1 * s1[2] + h1[2], v[1][j][7] * rs1 * s1[3] + h1[3]);
;             *(u32x4*)(XN + (size_t)row0 * D + c) = w0; *(u32x4*)(XN + (size_t)(row0 + 1) * D + c) = w1; }
	v_pk_fma_f32 v[20:21], v[20:21], v[4:5], v[12:13]
	v_pk_fma_f32 v[22:23], v[22:23], v[6:7], v[14:15]
	v_pk_fma_f32 v[8:9], v[24:25], v[0:1], v[8:9]
	v_pk_fma_f32 v[10:11], v[26:27], v[2:3], v[10:11]
	v_pk_fma_f32 v[12:13], v[28:29], v[4:5], v[12:13]
	v_pk_fma_f32 v[14:15], v[30:31], v[6:7], v[14:15]
	v_cvt_pk_bf16_f32 v0, v16, v17
	v_cvt_pk_bf16_f32 v1, v18, v19
	v_cvt_pk_bf16_f32 v2, v20, v21
	v_cvt_pk_bf16_f32 v3, v22, v23
	v_cvt_pk_bf16_f32 v4, v8, v9
	v_cvt_pk_bf16_f32 v5, v10, v11
	v_cvt_pk_bf16_f32 v6, v12, v13
	v_cvt_pk_bf16_f32 v7, v14, v15
	global_store_dwordx4 v[90:91], v[0:3], off offset:-1024
	global_store_dwordx4 v[78:79], v[4:7], off offset:-1024
	global_load_dwordx4 v[0:3], v88, s[14:15]
	s_nop 0
	global_load_dwordx4 v[4:7], v88, s[14:15] offset:16
	global_load_dwordx4 v[8:11], v88, s[12:13]
	global_load_dwordx4 v[12:15], v88, s[12:13] offset:16
	v_pk_mul_f32 v[16:17], v[48:49], v[106:107] op_sel_hi:[1,0]
	v_pk_mul_f32 v[18:19], v[50:51], v[106:107] op_sel_hi:[1,0]
	v_pk_mul_f32 v[20:21], v[52:53], v[106:107] op_sel_hi:[1,0]
	v_pk_mul_f32 v[22:23], v[54:55], v[106:107] op_sel_hi:[1,0]
	v_pk_mul_f32 v[24:25], v[56:57], v[108:109] op_sel_hi:[1,0]
	v_pk_mul_f32 v[26:27], v[58:59], v[108:109] op_sel_hi:[1,0]
	v_pk_mul_f32 v[28:29], v[60:61], v[108:109] op_sel_hi:[1,0]
	v_pk_mul_f32 v[30:31], v[62:63], v[108:109] op_sel_hi:[1,0]
	s_waitcnt vmcnt(3)
	v_pk_add_f32 v[2:3], v[2:3], 1.0 op_sel_hi:[1,0]
	v_pk_add_f32 v[0:1], v[0:1], 1.0 op_sel_hi:[1,0]
	s_waitcnt vmcnt(2)
	v_pk_add_f32 v[6:7], v[6:7], 1.0 op_sel_hi:[1,0]
	v_pk_add_f32 v[4:5], v[4:5], 1.0 op_sel_hi:[1,0]
	s_waitcnt vmcnt(1)
	v_pk_fma_f32 v[16:17], v[16:17], v[0:1], v[8:9]
	v_pk_fma_f32 v[18:19], v[18:19], v[2:3], v[10:11]
	s_waitcnt vmcnt(0)
	v_pk_fma_f32 v[20:21], v[20:21], v[4:5], v[12:13]
	v_pk_fma_f32 v[22:23], v[22:23], v[6:7], v[14:15]
	v_pk_fma_f32 v[8:9], v[24:25], v[0:1], v[8:9]
	v_pk_fma_f32 v[10:11], v[26:27], v[2:3], v[10:11]
	v_pk_fma_f32 v[12:13], v[28:29], v[4:5], v[12:13]
	v_pk_fma_f32 v[14:15], v[30:31], v[6:7], v[14:15]
	v_cvt_pk_bf16_f32 v0, v16, v17
	v_cvt_pk_bf16_f32 v1, v18, v19
	v_cvt_pk_bf16_f32 v2, v20, v21
	v_cvt_pk_bf16_f32 v3, v22, v23
	v_cvt_pk_bf16_f32 v4, v8, v9
	v_cvt_pk_bf16_f32 v5, v10, v11
	v_cvt_pk_bf16_f32 v6, v12, v13
	v_cvt_pk_bf16_f32 v7, v14, v15
	global_store_dwordx4 v[78:79], v[0:3], off offset:-4096
	global_store_dwordx4 v[78:79], v[4:7], off
	v_lshl_add_u64 v[78:79], v[78:79], 0, s[8:9]
	s_cbranch_scc1 .LBB0_829
.LBB0_797:
	v_readlane_b32 s0, v254, 41
	s_cmp_lt_i32 s4, s0
	v_readlane_b32 s0, v254, 38
	s_cselect_b32 s2, s77, s0
	v_readlane_b32 s0, v254, 36
	v_readlane_b32 s1, v254, 40
	s_cselect_b32 s3, s0, s1
	s_add_u32 s0, s10, -1
	s_addc_u32 s1, s11, -1
	s_lshl_b64 s[0:1], s[0:1], s18
	v_readlane_b32 s12, v254, 31
	s_add_u32 s0, s3, s0
	v_readlane_b32 s13, v254, 32
	s_addc_u32 s1, s2, s1
	s_mov_b64 s[2:3], -1
	s_and_b64 vcc, exec, s[12:13]
	s_cbranch_vccz .LBB0_799
	v_lshl_add_u64 v[0:1], s[0:1], 0, v[64:65]
	global_load_dwordx4 v[0:3], v[0:1], off
	s_mov_b64 s[2:3], 0
.LBB0_799:
	s_andn2_b64 vcc, exec, s[2:3]
	s_cbranch_vccnz .LBB0_801
	v_lshl_add_u64 v[4:5], s[0:1], 0, v[160:161]
	global_load_dwordx4 v[0:3], v[4:5], off offset:16
	s_nop 0
	global_load_dwordx4 v[4:7], v[4:5], off
.LBB0_801:
	v_readlane_b32 s2, v254, 41
	s_cmp_lt_i32 s10, s2
	v_readlane_b32 s2, v254, 38
	s_cselect_b32 s5, s77, s2
	v_readlane_b32 s2, v254, 36
	v_readlane_b32 s3, v254, 40
	s_cselect_b32 s12, s2, s3
	s_lshl_b64 s[2:3], s[10:11], s18
	v_readlane_b32 s14, v254, 31
	s_add_u32 s12, s12, s2
	v_readlane_b32 s15, v254, 32
	s_addc_u32 s13, s5, s3
	s_mov_b64 s[2:3], -1
	s_and_b64 vcc, exec, s[14:15]
	s_cbranch_vccz .LBB0_803
	v_lshl_add_u64 v[8:9], s[12:13], 0, v[64:65]
	global_load_dwordx4 v[8:11], v[8:9], off
	s_mov_b64 s[2:3], 0
.LBB0_803:
	s_andn2_b64 vcc, exec, s[2:3]
	s_cbranch_vccnz .LBB0_805
	v_lshl_add_u64 v[12:13], s[12:13], 0, v[160:161]
	global_load_dwordx4 v[8:11], v[12:13], off offset:16
	s_nop 0
	global_load_dwordx4 v[12:15], v[12:13], off
.LBB0_805:
	v_readlane_b32 s14, v254, 31
	v_readlane_b32 s15, v254, 32
	s_mov_b64 s[2:3], -1
	s_and_b64 vcc, exec, s[14:15]
	s_cbranch_vccz .LBB0_807
	v_lshl_add_u64 v[16:17], s[0:1], 0, v[68:69]
	global_load_dwordx4 v[16:19], v[16:17], off
	s_mov_b64 s[2:3], 0
.LBB0_807:
	s_andn2_b64 vcc, exec, s[2:3]
	s_cbranch_vccnz .LBB0_809
	v_lshl_add_u64 v[20:21], s[0:1], 0, v[66:67]
	global_load_dwordx4 v[16:19], v[20:21], off offset:16
	s_nop 0
	global_load_dwordx4 v[20:23], v[20:21], off
.LBB0_809:
	v_readlane_b32 s14, v254, 31
	v_readlane_b32 s15, v254, 32
	s_mov_b64 s[2:3], -1
	s_and_b64 vcc, exec, s[14:15]
	s_cbranch_vccz .LBB0_811
	v_lshl_add_u64 v[24:25], s[12:13], 0, v[68:69]
	global_load_dwordx4 v[24:27], v[24:25], off
	s_mov_b64 s[2:3], 0
.LBB0_811:
	s_andn2_b64 vcc, exec, s[2:3]
	s_cbranch_vccnz .LBB0_813
	v_lshl_add_u64 v[28:29], s[12:13], 0, v[66:67]
	global_load_dwordx4 v[24:27], v[28:29], off offset:16
	s_nop 0
	global_load_dwordx4 v[28:31], v[28:29], off
.LBB0_813:
	v_readlane_b32 s14, v254, 31
	v_readlane_b32 s15, v254, 32
	s_mov_b64 s[2:3], -1
	s_and_b64 vcc, exec, s[14:15]
	s_cbranch_vccz .LBB0_815
	v_lshl_add_u64 v[32:33], s[0:1], 0, v[72:73]
	global_load_dwordx4 v[32:35], v[32:33], off
	s_mov_b64 s[2:3], 0
.LBB0_815:
	s_andn2_b64 vcc, exec, s[2:3]
	s_cbranch_vccnz .LBB0_817
	v_lshl_add_u64 v[36:37], s[0:1], 0, v[70:71]
	global_load_dwordx4 v[32:35], v[36:37], off offset:16
	s_nop 0
	global_load_dwordx4 v[36:39], v[36:37], off
.LBB0_817:
	v_readlane_b32 s14, v254, 31
	v_readlane_b32 s15, v254, 32
	s_mov_b64 s[2:3], -1
	s_and_b64 vcc, exec, s[14:15]
	s_cbranch_vccz .LBB0_819
	v_lshl_add_u64 v[40:41], s[12:13], 0, v[72:73]
	global_load_dwordx4 v[40:43], v[40:41], off
	s_mov_b64 s[2:3], 0
.LBB0_819:
	s_andn2_b64 vcc, exec, s[2:3]
	s_cbranch_vccnz .LBB0_821
	v_lshl_add_u64 v[44:45], s[12:13], 0, v[70:71]
	global_load_dwordx4 v[40:43], v[44:45], off offset:16
	s_nop 0
	global_load_dwordx4 v[44:47], v[44:45], off
.LBB0_821:
	v_readlane_b32 s14, v254, 31
	v_readlane_b32 s15, v254, 32
	s_mov_b64 s[2:3], -1
	s_and_b64 vcc, exec, s[14:15]
	s_cbranch_vccz .LBB0_823
	v_lshl_add_u64 v[48:49], s[0:1], 0, v[76:77]
	global_load_dwordx4 v[52:55], v[48:49], off
	s_mov_b64 s[2:3], 0
.LBB0_823:
	s_andn2_b64 vcc, exec, s[2:3]
	s_cbranch_vccnz .LBB0_825
	v_lshl_add_u64 v[48:49], s[0:1], 0, v[74:75]
	global_load_dwordx4 v[52:55], v[48:49], off offset:16
	s_nop 0
	global_load_dwordx4 v[48:51], v[48:49], off
.LBB0_825:
	v_readlane_b32 s2, v254, 31
	v_readlane_b32 s3, v254, 32
	s_mov_b64 s[0:1], -1
	s_and_b64 vcc, exec, s[2:3]
	s_cbranch_vccz .LBB0_827
	v_lshl_add_u64 v[56:57], s[12:13], 0, v[76:77]
	global_load_dwordx4 v[60:63], v[56:57], off
	s_mov_b64 s[0:1], 0
.LBB0_827:
	s_andn2_b64 vcc, exec, s[0:1]
	s_cbranch_vccnz .LBB0_796
	v_lshl_add_u64 v[56:57], s[12:13], 0, v[74:75]
	global_load_dwordx4 v[60:63], v[56:57], off offset:16
	s_nop 0
	global_load_dwordx4 v[56:59], v[56:57], off
	s_branch .LBB0_796
